# sgemm loads de-serialised + att1 parallel segment lookup + att1 load balance (list padding C=2)
# speedup vs baseline: 1.0193x; 1.0193x over previous
.LBB0_278:
	global_load_dwordx4 v[52:55], v[42:43], off
	v_lshl_or_b32 v16, s68, 5, v78
	v_ashrrev_i32_e32 v17, 31, v16
	v_lshlrev_b64 v[4:5], 11, v[16:17]
	v_lshl_add_u64 v[30:31], v[44:45], 0, v[4:5]
	global_load_dwordx4 v[92:95], v[30:31], off
	global_load_dwordx4 v[96:99], v[42:43], off offset:32
	global_load_dwordx4 v[100:103], v[30:31], off offset:32
	global_load_dwordx4 v[104:107], v[42:43], off offset:64
	global_load_dwordx4 v[108:111], v[30:31], off offset:64
	global_load_dwordx4 v[112:115], v[42:43], off offset:96
	v_add_u32_e32 v17, 0x8000, v80
	global_load_dwordx4 v[116:119], v[30:31], off offset:96
	global_load_dwordx4 v[120:123], v[42:43], off offset:128
	global_load_dwordx4 v[124:127], v[30:31], off offset:128
	global_load_dwordx4 v[128:131], v[42:43], off offset:160
	global_load_dwordx4 v[132:135], v[30:31], off offset:160
	global_load_dwordx4 v[136:139], v[42:43], off offset:192
	global_load_dwordx4 v[144:147], v[30:31], off offset:192
	global_load_dwordx4 v[148:151], v[42:43], off offset:224
	global_load_dwordx4 v[160:163], v[30:31], off offset:224
	global_load_dwordx2 v[20:21], v[38:39], off
	global_load_dwordx2 v[18:19], v[40:41], off
	v_add_u32_e32 v22, 0x8400, v80
	v_add_u32_e32 v23, 0x8800, v80
	v_add_u32_e32 v24, 0x8c00, v80
	s_waitcnt vmcnt(16)
	v_mfma_f32_32x32x16_bf16 v[0:15], v[52:55], v[92:95], 0
	s_waitcnt vmcnt(14)
	v_mfma_f32_32x32x16_bf16 v[0:15], v[96:99], v[100:103], v[0:15]
	s_waitcnt vmcnt(12)
	v_mfma_f32_32x32x16_bf16 v[0:15], v[104:107], v[108:111], v[0:15]
	s_waitcnt vmcnt(10)
	v_mfma_f32_32x32x16_bf16 v[0:15], v[112:115], v[116:119], v[0:15]
	s_waitcnt vmcnt(8)
	v_mfma_f32_32x32x16_bf16 v[0:15], v[120:123], v[124:127], v[0:15]
	s_waitcnt vmcnt(6)
	v_mfma_f32_32x32x16_bf16 v[0:15], v[128:131], v[132:135], v[0:15]
	s_waitcnt vmcnt(4)
	v_mfma_f32_32x32x16_bf16 v[0:15], v[136:139], v[144:147], v[0:15]
	s_waitcnt vmcnt(2)
	v_mfma_f32_32x32x16_bf16 v[0:15], v[148:151], v[160:163], v[0:15]
	s_waitcnt vmcnt(0)
	s_nop 11
	ds_write2_b32 v17, v0, v1 offset1:32
	ds_write2_b32 v17, v2, v3 offset0:64 offset1:96
	ds_write2_b32 v22, v4, v5 offset1:32
	ds_write2_b32 v22, v6, v7 offset0:64 offset1:96
	ds_write2_b32 v23, v8, v9 offset1:32
	ds_write2_b32 v23, v10, v11 offset0:64 offset1:96
	ds_write2_b32 v24, v12, v13 offset1:32
	ds_write2_b32 v24, v14, v15 offset0:64 offset1:96
	s_waitcnt lgkmcnt(0)
	s_barrier
	s_and_saveexec_b64 s[40:41], s[34:35]
	s_movk_i32 s12, 0x1ff
	s_movk_i32 s28, 0x1080
	s_cbranch_execz .LBB0_281
	s_mov_b64 s[2:3], 0
	v_mov_b32_e32 v0, v64

.LBB0_934:
	v_readlane_b32 s2, v254, 24
	v_cmp_gt_i32_e32 vcc, 8, v138
	s_nop 0
	v_lshl_add_u32 v9, v138, 2, s2
	s_waitcnt vmcnt(0) lgkmcnt(0)
	s_barrier
	s_and_saveexec_b64 s[2:3], vcc
	ds_write_b32 v9, v33
	s_or_b64 exec, exec, s[2:3]
	v_and_b32_e32 v14, 64, v216
	v_add_u32_e32 v16, -1, v216
	v_cmp_lt_i32_e32 vcc, v16, v14
	v_add_u32_e32 v17, -2, v216
	v_add_u32_e32 v10, 0x7f, v12
	v_cndmask_b32_e32 v16, v16, v216, vcc
	v_cmp_lt_i32_e32 vcc, v17, v14
	v_add_u32_e32 v18, -4, v216
	v_ashrrev_i32_e32 v15, 7, v10
	v_min_u32_e32 v10, 1, v12
	v_lshl_add_u32 v15, v10, 1, v15
	v_lshlrev_b32_e32 v16, 2, v16
	v_cndmask_b32_e32 v17, v17, v216, vcc
	v_cmp_lt_i32_e32 vcc, v18, v14
	v_add_u32_e32 v19, -8, v216
	v_add_u32_e32 v20, -16, v216
	v_cndmask_b32_e32 v18, v18, v216, vcc
	v_cmp_lt_i32_e32 vcc, v19, v14
	ds_bpermute_b32 v16, v16, v15
	v_subrev_u32_e32 v21, 32, v216
	v_cndmask_b32_e32 v19, v19, v216, vcc
	v_cmp_lt_i32_e32 vcc, v20, v14
	v_and_b32_e32 v10, 63, v138
	v_lshlrev_b32_e32 v17, 2, v17
	v_cndmask_b32_e32 v20, v20, v216, vcc
	v_cmp_lt_i32_e32 vcc, v21, v14
	v_lshlrev_b32_e32 v18, 2, v18
	v_lshlrev_b32_e32 v19, 2, v19
	v_cndmask_b32_e32 v21, v21, v216, vcc
	v_cmp_eq_u32_e32 vcc, 63, v10
	s_and_b64 s[4:5], s[40:41], vcc
	v_cmp_ne_u32_e32 vcc, 0, v10
	v_lshlrev_b32_e32 v20, 2, v20
	v_cmp_gt_u32_e64 s[38:39], 16, v10
	s_waitcnt lgkmcnt(0)
	v_cndmask_b32_e32 v16, 0, v16, vcc
	v_add_u32_e32 v15, v16, v15
	ds_bpermute_b32 v16, v17, v15
	v_cmp_lt_u32_e32 vcc, 1, v10
	v_lshlrev_b32_e32 v21, 2, v21
	s_ashr_i32 s11, s20, 6
	s_waitcnt lgkmcnt(0)
	v_cndmask_b32_e32 v16, 0, v16, vcc
	v_add_u32_e32 v15, v16, v15
	ds_bpermute_b32 v16, v18, v15
	v_cmp_lt_u32_e32 vcc, 3, v10
	s_waitcnt lgkmcnt(0)
	s_nop 0
	v_cndmask_b32_e32 v16, 0, v16, vcc
	v_add_u32_e32 v15, v16, v15
	ds_bpermute_b32 v16, v19, v15
	v_cmp_lt_u32_e32 vcc, 7, v10
	s_waitcnt lgkmcnt(0)
	s_nop 0
	v_cndmask_b32_e32 v16, 0, v16, vcc
	v_add_u32_e32 v15, v16, v15
	ds_bpermute_b32 v16, v20, v15
	v_cmp_lt_u32_e32 vcc, 31, v10
	s_waitcnt lgkmcnt(0)
	v_cndmask_b32_e64 v16, v16, 0, s[38:39]
	v_add_u32_e32 v15, v16, v15
	ds_bpermute_b32 v16, v21, v15
	s_waitcnt lgkmcnt(0)
	v_cndmask_b32_e32 v16, 0, v16, vcc
	v_add_u32_e32 v15, v16, v15
	s_and_saveexec_b64 s[2:3], s[4:5]
	s_cbranch_execz .LBB0_989
	s_lshl_b32 s4, s11, 2
	s_add_i32 s4, s4, 0
	s_add_i32 s4, s4, 0x21410
	v_mov_b32_e32 v16, s4
	ds_write_b32 v16, v15
	s_or_b64 exec, exec, s[2:3]
	s_and_saveexec_b64 s[2:3], s[40:41]
	s_cbranch_execnz .LBB0_990

.LBB0_968:
	s_waitcnt vmcnt(5)
	v_mbcnt_lo_u32_b32 v8, -1, 0
	v_mbcnt_hi_u32_b32 v8, -1, v8
	v_lshlrev_b32_e32 v8, 4, v8
	v_add_u32_e32 v8, 0x21004, v8
	ds_read2_b32 v[10:11], v8 offset1:1
	ds_read2_b32 v[8:9], v8 offset0:2 offset1:3
	s_waitcnt lgkmcnt(0)
	v_cmp_ge_i32_e32 vcc, s48, v10
	s_bcnt1_i32_b64 s40, vcc
	v_cmp_ge_i32_e32 vcc, s48, v11
	s_bcnt1_i32_b64 s2, vcc
	s_add_i32 s40, s40, s2
	v_cmp_ge_i32_e32 vcc, s48, v8
	s_bcnt1_i32_b64 s2, vcc
	s_add_i32 s40, s40, s2
	v_cmp_ge_i32_e32 vcc, s48, v9
	s_bcnt1_i32_b64 s2, vcc
	s_add_i32 s40, s40, s2
	s_lshl_b32 s2, s40, 2
	s_add_i32 s2, s2, 0x21004
	v_mov_b32_e32 v8, s2
	ds_read_b32 v8, v8
	s_waitcnt lgkmcnt(0)
	v_readfirstlane_b32 s20, v8
	s_lshl_b32 s2, s40, 2
	s_add_i32 s2, s2, 0
	s_add_i32 s3, s2, 0x21c00
	v_mov_b32_e32 v8, s3
	s_add_i32 s2, s2, 0x21000
	v_mov_b32_e32 v9, s2
	ds_read_b32 v8, v8
	ds_read_b32 v130, v9
	s_min_i32 s21, s20, s0
	s_ashr_i32 s41, s40, 31
	s_ashr_i32 s31, s40, 7
	s_bfe_u32 s43, s40, 0x20005
	s_waitcnt lgkmcnt(0)
	v_readfirstlane_b32 s2, v130
	s_sub_i32 s3, s48, s2
	s_sub_i32 s2, s21, s2
	s_lshl_b32 s23, s3, 7
	s_lshl_b32 s2, s2, 7
	v_readfirstlane_b32 s3, v8
	s_min_i32 s28, s2, s3
	s_sub_i32 s2, s28, s23
	s_add_i32 s2, s2, 15
	s_ashr_i32 s29, s2, 4
	s_cmp_lt_i32 s29, 1
	s_cbranch_scc1 .LBB0_987
	s_lshl_b64 s[2:3], s[40:41], 16
	s_add_u32 s46, s1, s2
	s_addc_u32 s47, s12, s3
	s_cmp_lt_i32 s11, s29
	s_cselect_b64 s[50:51], -1, 0
	s_and_b64 s[2:3], s[50:51], exec
	s_cselect_b32 s2, s11, 0
	s_cmp_lt_i32 s19, s29
	s_cselect_b32 s3, s19, s2
	s_lshl_b32 s2, s2, 4
	s_add_i32 s2, s2, s23
	v_or_b32_e32 v8, s2, v132
	v_mov_b32_e32 v9, s2
	s_lshl_b32 s2, s3, 4
	s_add_i32 s2, s2, s23
	v_cmp_gt_i32_e32 vcc, s28, v8
	v_or_b32_e32 v10, s2, v132
	v_mov_b32_e32 v11, s2
	v_cndmask_b32_e32 v8, v9, v8, vcc
	v_cmp_gt_i32_e32 vcc, s28, v10
	v_ashrrev_i32_e32 v9, 31, v8
	v_lshl_add_u64 v[8:9], v[8:9], 2, s[46:47]
	v_cndmask_b32_e32 v10, v11, v10, vcc
	v_ashrrev_i32_e32 v11, 31, v10
	v_lshl_add_u64 v[10:11], v[10:11], 2, s[46:47]
	global_load_dword v220, v[8:9], off
	global_load_dword v230, v[10:11], off
	s_lshl_b32 s2, s40, 8
	s_lshl_b32 s30, s31, 13
	s_and_b32 s41, s2, 0x1f00
	s_or_b32 s2, s41, s30
	s_ashr_i32 s3, s2, 31
	s_lshl_b64 s[2:3], s[2:3], 10
	s_add_u32 s2, s8, s2
	s_addc_u32 s3, s13, s3
	s_lshl_b32 s49, s43, 8
	s_add_u32 s2, s2, s49
	s_addc_u32 s3, s3, 0
	v_lshl_add_u64 v[8:9], s[2:3], 0, v[142:143]
	v_lshlrev_b32_e32 v32, 1, v190
	v_lshl_add_u64 v[10:11], s[2:3], 0, v[144:145]
	v_lshl_add_u64 v[8:9], v[8:9], 0, v[32:33]
	v_lshl_add_u64 v[10:11], v[10:11], 0, v[32:33]
	s_lshl_b32 s31, s31, 2
	global_load_dwordx4 v[50:53], v[8:9], off
	global_load_dwordx4 v[46:49], v[10:11], off
	v_lshl_add_u64 v[8:9], s[2:3], 0, v[146:147]
	v_lshl_add_u64 v[10:11], s[2:3], 0, v[148:149]
	s_or_b32 s52, s31, s43
	v_lshl_add_u64 v[8:9], v[8:9], 0, v[32:33]
	v_lshl_add_u64 v[10:11], v[10:11], 0, v[32:33]
	s_ashr_i32 s53, s52, 31
	global_load_dwordx4 v[58:61], v[8:9], off
	global_load_dwordx4 v[54:57], v[10:11], off
	v_lshl_add_u64 v[8:9], s[2:3], 0, v[150:151]
	v_lshl_add_u64 v[10:11], s[2:3], 0, v[152:153]
	s_lshl_b64 s[52:53], s[52:53], 21
	v_lshl_add_u64 v[8:9], v[8:9], 0, v[32:33]
	v_lshl_add_u64 v[10:11], v[10:11], 0, v[32:33]
	global_load_dwordx4 v[70:73], v[8:9], off
	global_load_dwordx4 v[66:69], v[10:11], off
	v_lshl_add_u64 v[8:9], s[2:3], 0, v[164:165]
	v_lshl_add_u64 v[10:11], s[2:3], 0, v[168:169]
	s_add_u32 s2, s14, s52
	s_addc_u32 s3, s15, s53
	s_lshl_b32 s31, s41, 1
	s_add_u32 s2, s2, s31
	v_lshl_add_u64 v[8:9], v[8:9], 0, v[32:33]
	s_addc_u32 s3, s3, 0
	v_lshl_add_u64 v[10:11], v[10:11], 0, v[32:33]
	global_load_dwordx4 v[78:81], v[8:9], off
	global_load_dwordx4 v[74:77], v[10:11], off
	v_lshl_add_u64 v[8:9], s[2:3], 0, v[162:163]
	v_mov_b32_e32 v183, v33
	v_lshl_add_u64 v[8:9], v[8:9], 0, v[182:183]
	v_lshl_add_u64 v[10:11], s[2:3], 0, v[166:167]
	v_lshl_add_u64 v[10:11], v[10:11], 0, v[182:183]
	global_load_dwordx4 v[86:89], v[8:9], off
	global_load_dwordx4 v[82:85], v[10:11], off
	v_lshl_add_u64 v[8:9], s[2:3], 0, v[170:171]
	v_lshl_add_u64 v[8:9], v[8:9], 0, v[182:183]
	v_lshl_add_u64 v[10:11], s[2:3], 0, v[172:173]
	v_lshl_add_u64 v[10:11], v[10:11], 0, v[182:183]
	global_load_dwordx4 v[94:97], v[8:9], off
	global_load_dwordx4 v[90:93], v[10:11], off
	v_lshl_add_u64 v[8:9], s[2:3], 0, v[174:175]
	v_lshl_add_u64 v[8:9], v[8:9], 0, v[182:183]
	v_lshl_add_u64 v[10:11], s[2:3], 0, v[176:177]
	v_lshl_add_u64 v[10:11], v[10:11], 0, v[182:183]
	global_load_dwordx4 v[102:105], v[8:9], off
	global_load_dwordx4 v[98:101], v[10:11], off
	v_lshl_add_u64 v[8:9], s[2:3], 0, v[178:179]
	v_lshl_add_u64 v[8:9], v[8:9], 0, v[182:183]
	v_lshl_add_u64 v[10:11], s[2:3], 0, v[180:181]
	v_lshl_add_u64 v[10:11], v[10:11], 0, v[182:183]
	global_load_dwordx4 v[110:113], v[8:9], off
	global_load_dwordx4 v[106:109], v[10:11], off
	s_waitcnt vmcnt(17)
	v_and_b32_e32 v8, 0x1fff, v220
	v_or_b32_e32 v8, s30, v8
	v_ashrrev_i32_e32 v9, 31, v8
	s_lshl_b32 s31, s43, 1
	v_lshrrev_b32_e32 v10, 13, v220
	s_min_i32 s2, s17, 47
	v_lshlrev_b64 v[8:9], 11, v[8:9]
	v_and_or_b32 v10, v10, 1, s31
	s_ashr_i32 s3, s2, 3
	v_lshl_add_u64 v[8:9], s[4:5], 0, v[8:9]
	v_lshlrev_b32_e32 v32, 8, v10
	s_lshl_b32 s3, s3, 2
	v_readlane_b32 s18, v254, 24
	v_lshl_add_u64 v[8:9], v[8:9], 0, v[32:33]
	v_mov_b32_e32 v129, v33
	s_add_i32 s3, s18, s3
	v_lshl_add_u64 v[20:21], v[8:9], 0, v[128:129]
	v_mov_b32_e32 v24, s3
	global_load_dwordx4 v[8:11], v[20:21], off
	global_load_dwordx4 v[12:15], v[20:21], off offset:64
	global_load_dwordx4 v[16:19], v[20:21], off offset:128
	s_nop 0
	global_load_dwordx4 v[20:23], v[20:21], off offset:192
	ds_read_b32 v24, v24
	s_lshl_b32 s2, s2, 4
	s_and_b32 s2, s2, 0x70
	v_readlane_b32 s52, v251, 1
	v_readlane_b32 s56, v251, 5
	s_waitcnt lgkmcnt(0)
	v_lshlrev_b32_e32 v24, 7, v24
	v_or_b32_e32 v24, s2, v24
	s_min_i32 s2, s17, 46
	s_add_i32 s2, s2, 1
	s_ashr_i32 s3, s2, 3
	s_lshl_b32 s3, s3, 2
	v_add_u32_e32 v24, v24, v186
	s_add_i32 s3, s18, s3
	v_ashrrev_i32_e32 v25, 31, v24
	v_mov_b32_e32 v28, s3
	v_lshlrev_b64 v[24:25], 11, v[24:25]
	ds_read_b32 v28, v28
	v_or_b32_e32 v24, v24, v227
	v_readlane_b32 s57, v251, 6
	s_lshl_b32 s2, s2, 4
	s_and_b32 s2, s2, 0x70
	v_lshl_add_u64 v[26:27], s[56:57], 0, v[24:25]
	global_load_dwordx4 v[62:65], v[26:27], off
	s_waitcnt lgkmcnt(0)
	v_lshlrev_b32_e32 v28, 7, v28
	v_or_b32_e32 v28, s2, v28
	s_min_i32 s2, s17, 45
	s_add_i32 s2, s2, 2
	s_ashr_i32 s3, s2, 3
	s_lshl_b32 s3, s3, 2
	s_add_i32 s3, s18, s3
	v_mov_b32_e32 v32, s3
	ds_read_b32 v32, v32
	s_lshl_b32 s2, s2, 4
	s_and_b32 s2, s2, 0x70
	v_add_u32_e32 v28, v28, v186
	v_ashrrev_i32_e32 v29, 31, v28
	s_waitcnt lgkmcnt(0)
	v_lshlrev_b32_e32 v32, 7, v32
	v_or_b32_e32 v32, s2, v32
	s_min_i32 s2, s17, 44
	s_add_i32 s2, s2, 3
	s_ashr_i32 s3, s2, 3
	s_lshl_b32 s3, s3, 2
	s_add_i32 s3, s18, s3
	v_add_u32_e32 v34, v32, v186
	v_mov_b32_e32 v32, s3
	ds_read_b32 v32, v32
	s_lshl_b32 s2, s2, 4
	s_and_b32 s2, s2, 0x70
	v_ashrrev_i32_e32 v35, 31, v34
	v_lshlrev_b64 v[28:29], 11, v[28:29]
	s_waitcnt lgkmcnt(0)
	v_lshlrev_b32_e32 v32, 7, v32
	v_or_b32_e32 v32, s2, v32
	v_add_u32_e32 v114, v32, v186
	v_ashrrev_i32_e32 v115, 31, v114
	v_lshlrev_b64 v[34:35], 11, v[34:35]
	v_lshlrev_b64 v[114:115], 11, v[114:115]
	v_readlane_b32 s58, v251, 7
	v_readlane_b32 s59, v251, 8
	v_or_b32_e32 v28, v28, v227
	v_or_b32_e32 v34, v34, v227
	v_or_b32_e32 v114, v114, v227
	v_lshl_add_u64 v[24:25], s[58:59], 0, v[24:25]
	v_lshl_add_u64 v[30:31], s[56:57], 0, v[28:29]
	v_lshl_add_u64 v[28:29], s[58:59], 0, v[28:29]
	v_lshl_add_u64 v[36:37], s[56:57], 0, v[34:35]
	v_lshl_add_u64 v[34:35], s[58:59], 0, v[34:35]
	v_lshl_add_u64 v[116:117], s[56:57], 0, v[114:115]
	v_lshl_add_u64 v[114:115], s[58:59], 0, v[114:115]
	global_load_dwordx4 v[38:41], v[30:31], off
	global_load_dwordx4 v[42:45], v[36:37], off
	global_load_dwordx4 v[118:121], v[116:117], off
	v_add_u32_e32 v32, v187, v196
	global_load_dwordx4 v[24:27], v[24:25], off
	s_cmp_gt_i32 s17, 47
	global_load_dwordx4 v[28:31], v[28:29], off
	v_readlane_b32 s53, v251, 2
	global_load_dwordx4 v[34:37], v[34:35], off
	v_readlane_b32 s54, v251, 3
	global_load_dwordx4 v[114:117], v[114:115], off
	s_barrier
	s_waitcnt vmcnt(27)
	ds_write_b128 v32, v[50:53]
	v_add_u32_e32 v32, v195, v198
	s_waitcnt vmcnt(26)
	ds_write_b128 v32, v[46:49]
	v_add_u32_e32 v32, v197, v200
	s_waitcnt vmcnt(25)
	ds_write_b128 v32, v[58:61]
	v_add_u32_e32 v32, v199, v203
	s_waitcnt vmcnt(24)
	ds_write_b128 v32, v[54:57]
	v_add_u32_e32 v32, v202, v205
	s_waitcnt vmcnt(23)
	ds_write_b128 v32, v[70:73]
	v_add_u32_e32 v32, v204, v207
	s_waitcnt vmcnt(22)
	ds_write_b128 v32, v[66:69]
	v_add_u32_e32 v32, v206, v209
	s_waitcnt vmcnt(21)
	ds_write_b128 v32, v[78:81]
	v_add_u32_e32 v32, v208, v210
	s_waitcnt vmcnt(20)
	ds_write_b128 v32, v[74:77]
	v_add_u32_e32 v32, v211, v201
	s_waitcnt vmcnt(19)
	ds_write_b128 v32, v[86:89]
	v_add_u32_e32 v32, v212, v201
	s_waitcnt vmcnt(18)
	ds_write_b128 v32, v[82:85]
	v_add_u32_e32 v32, v213, v201
	s_waitcnt vmcnt(17)
	ds_write_b128 v32, v[94:97]
	v_add_u32_e32 v32, v221, v201
	s_waitcnt vmcnt(16)
	ds_write_b128 v32, v[90:93]
	v_add_u32_e32 v32, v222, v201
	s_waitcnt vmcnt(15)
	ds_write_b128 v32, v[102:105]
	v_add_u32_e32 v32, v223, v201
	s_waitcnt vmcnt(14)
	ds_write_b128 v32, v[98:101]
	v_add_u32_e32 v32, v224, v201
	s_waitcnt vmcnt(13)
	ds_write_b128 v32, v[110:113]
	v_add_u32_e32 v32, v225, v201
	s_waitcnt vmcnt(12)
	ds_write_b128 v32, v[106:109]
	s_waitcnt vmcnt(7)
	v_mul_f32_e32 v32, v1, v63
	v_fmac_f32_e32 v32, v0, v62
	v_fmac_f32_e32 v32, v2, v64
	v_fmac_f32_e32 v32, v3, v65
	ds_bpermute_b32 v46, v191, v32
	v_readlane_b32 s55, v251, 4
	v_readlane_b32 s60, v251, 9
	v_readlane_b32 s61, v251, 10
	v_readlane_b32 s62, v251, 11
	s_waitcnt lgkmcnt(0)
	v_add_f32_e32 v32, v32, v46
	ds_bpermute_b32 v46, v192, v32
	v_readlane_b32 s63, v251, 12
	v_readlane_b32 s64, v251, 13
	v_readlane_b32 s65, v251, 14
	v_readlane_b32 s66, v251, 15
	s_waitcnt lgkmcnt(0)
	v_add_f32_e32 v32, v32, v46
	ds_bpermute_b32 v46, v193, v32
	v_readlane_b32 s67, v251, 16
	s_waitcnt lgkmcnt(0)
	s_barrier
	v_add_f32_e32 v32, v32, v46
	ds_bpermute_b32 v46, v194, v32
	s_waitcnt lgkmcnt(0)
	v_add_f32_e32 v32, v32, v46
	ds_bpermute_b32 v46, v226, v32
	s_cbranch_scc1 .LBB0_972
	s_waitcnt lgkmcnt(0)
	v_add_f32_e32 v32, v32, v46
	v_max_f32_e32 v46, v188, v188
	v_max_f32_e32 v47, v46, v32
	v_sub_f32_e32 v32, v32, v47
	v_sub_f32_e32 v46, v188, v47
	v_exp_f32_e32 v32, v32
	v_exp_f32_e32 v46, v46
	v_mov_b32_e32 v188, v47
	v_mov_b32_e32 v48, v32
	v_fmac_f32_e32 v48, v189, v46
	s_waitcnt vmcnt(3)
	v_pk_mul_f32 v[24:25], v[24:25], v[32:33] op_sel_hi:[1,0]
	v_pk_mul_f32 v[26:27], v[26:27], v[32:33] op_sel_hi:[1,0]
	v_pk_fma_f32 v[4:5], v[4:5], v[46:47], v[24:25] op_sel_hi:[1,0,1]
	v_pk_fma_f32 v[6:7], v[6:7], v[46:47], v[26:27] op_sel_hi:[1,0,1]
	v_mov_b32_e32 v189, v48

.LBB0_1338:
	global_load_dwordx4 v[64:67], v[38:39], off
	v_lshl_or_b32 v16, s29, 5, v81
	v_ashrrev_i32_e32 v17, 31, v16
	v_lshlrev_b64 v[4:5], 11, v[16:17]
	v_lshl_add_u64 v[30:31], v[40:41], 0, v[4:5]
	global_load_dwordx4 v[88:91], v[30:31], off
	global_load_dwordx4 v[92:95], v[38:39], off offset:32
	global_load_dwordx4 v[96:99], v[30:31], off offset:32
	global_load_dwordx4 v[100:103], v[38:39], off offset:64
	global_load_dwordx4 v[104:107], v[30:31], off offset:64
	global_load_dwordx4 v[108:111], v[38:39], off offset:96
	global_load_dwordx4 v[112:115], v[30:31], off offset:96
	global_load_dwordx4 v[116:119], v[38:39], off offset:128
	global_load_dwordx4 v[120:123], v[30:31], off offset:128
	global_load_dwordx4 v[124:127], v[38:39], off offset:160
	global_load_dwordx4 v[128:131], v[30:31], off offset:160
	global_load_dwordx4 v[132:135], v[38:39], off offset:192
	global_load_dwordx4 v[136:139], v[30:31], off offset:192
	global_load_dwordx4 v[140:143], v[38:39], off offset:224
	global_load_dwordx4 v[144:147], v[30:31], off offset:224
	v_add_u32_e32 v18, v16, v82
	v_add_u32_e32 v20, 0x4000, v18
	v_ashrrev_i32_e32 v19, 31, v18
	v_ashrrev_i32_e32 v21, 31, v20
	v_lshl_add_u64 v[18:19], v[18:19], 2, s[46:47]
	v_lshl_add_u64 v[20:21], v[20:21], 2, s[46:47]
	global_load_dword v18, v[18:19], off
	s_nop 0
	global_load_dword v17, v[20:21], off
	v_add_u32_e32 v19, 0x8000, v84
	v_add_u32_e32 v20, 0x8400, v84
	v_add_u32_e32 v21, 0x8800, v84
	v_add_u32_e32 v22, 0x8c00, v84
	s_waitcnt vmcnt(16)
	v_mfma_f32_32x32x16_bf16 v[0:15], v[64:67], v[88:91], 0
	s_waitcnt vmcnt(14)
	v_mfma_f32_32x32x16_bf16 v[0:15], v[92:95], v[96:99], v[0:15]
	s_waitcnt vmcnt(12)
	v_mfma_f32_32x32x16_bf16 v[0:15], v[100:103], v[104:107], v[0:15]
	s_waitcnt vmcnt(10)
	v_mfma_f32_32x32x16_bf16 v[0:15], v[108:111], v[112:115], v[0:15]
	s_waitcnt vmcnt(8)
	v_mfma_f32_32x32x16_bf16 v[0:15], v[116:119], v[120:123], v[0:15]
	s_waitcnt vmcnt(6)
	v_mfma_f32_32x32x16_bf16 v[0:15], v[124:127], v[128:131], v[0:15]
	s_waitcnt vmcnt(4)
	v_mfma_f32_32x32x16_bf16 v[0:15], v[132:135], v[136:139], v[0:15]
	s_waitcnt vmcnt(2)
	v_mfma_f32_32x32x16_bf16 v[0:15], v[140:143], v[144:147], v[0:15]
	s_waitcnt vmcnt(0)
	s_nop 11
	ds_write2_b32 v19, v0, v1 offset1:32
	ds_write2_b32 v19, v2, v3 offset0:64 offset1:96
	ds_write2_b32 v20, v4, v5 offset1:32
	ds_write2_b32 v20, v6, v7 offset0:64 offset1:96
	ds_write2_b32 v21, v8, v9 offset1:32
	ds_write2_b32 v21, v10, v11 offset0:64 offset1:96
	ds_write2_b32 v22, v12, v13 offset1:32
	ds_write2_b32 v22, v14, v15 offset0:64 offset1:96
	s_waitcnt lgkmcnt(0)
	s_barrier
	s_and_saveexec_b64 s[38:39], s[34:35]
	s_movk_i32 s41, 0x1ff
	s_movk_i32 s42, 0x1080
	s_cbranch_execz .LBB0_1341
	s_mov_b64 s[2:3], 0
	v_mov_b32_e32 v0, v43

.LBB0_1604:
	global_load_dwordx4 v[52:55], v[42:43], off
	v_lshl_or_b32 v16, s57, 5, v78
	v_ashrrev_i32_e32 v17, 31, v16
	v_lshlrev_b64 v[4:5], 11, v[16:17]
	v_lshl_add_u64 v[30:31], v[44:45], 0, v[4:5]
	global_load_dwordx4 v[88:91], v[30:31], off
	global_load_dwordx4 v[92:95], v[42:43], off offset:32
	global_load_dwordx4 v[96:99], v[30:31], off offset:32
	global_load_dwordx4 v[100:103], v[42:43], off offset:64
	global_load_dwordx4 v[104:107], v[30:31], off offset:64
	global_load_dwordx4 v[108:111], v[42:43], off offset:96
	v_add_u32_e32 v17, 0x8000, v80
	global_load_dwordx4 v[112:115], v[30:31], off offset:96
	global_load_dwordx4 v[116:119], v[42:43], off offset:128
	global_load_dwordx4 v[120:123], v[30:31], off offset:128
	global_load_dwordx4 v[124:127], v[42:43], off offset:160
	global_load_dwordx4 v[128:131], v[30:31], off offset:160
	global_load_dwordx4 v[132:135], v[42:43], off offset:192
	global_load_dwordx4 v[148:151], v[30:31], off offset:192
	global_load_dwordx4 v[160:163], v[42:43], off offset:224
	global_load_dwordx4 v[164:167], v[30:31], off offset:224
	global_load_dwordx2 v[20:21], v[38:39], off
	global_load_dwordx2 v[18:19], v[40:41], off
	v_add_u32_e32 v22, 0x8400, v80
	v_add_u32_e32 v23, 0x8800, v80
	v_add_u32_e32 v24, 0x8c00, v80
	s_waitcnt vmcnt(16)
	v_mfma_f32_32x32x16_bf16 v[0:15], v[52:55], v[88:91], 0
	s_waitcnt vmcnt(14)
	v_mfma_f32_32x32x16_bf16 v[0:15], v[92:95], v[96:99], v[0:15]
	s_waitcnt vmcnt(12)
	v_mfma_f32_32x32x16_bf16 v[0:15], v[100:103], v[104:107], v[0:15]
	s_waitcnt vmcnt(10)
	v_mfma_f32_32x32x16_bf16 v[0:15], v[108:111], v[112:115], v[0:15]
	s_waitcnt vmcnt(8)
	v_mfma_f32_32x32x16_bf16 v[0:15], v[116:119], v[120:123], v[0:15]
	s_waitcnt vmcnt(6)
	v_mfma_f32_32x32x16_bf16 v[0:15], v[124:127], v[128:131], v[0:15]
	s_waitcnt vmcnt(4)
	v_mfma_f32_32x32x16_bf16 v[0:15], v[132:135], v[148:151], v[0:15]
	s_waitcnt vmcnt(2)
	v_mfma_f32_32x32x16_bf16 v[0:15], v[160:163], v[164:167], v[0:15]
	s_waitcnt vmcnt(0)
	s_nop 11
	ds_write2_b32 v17, v0, v1 offset1:32
	ds_write2_b32 v17, v2, v3 offset0:64 offset1:96
	ds_write2_b32 v22, v4, v5 offset1:32
	ds_write2_b32 v22, v6, v7 offset0:64 offset1:96
	ds_write2_b32 v23, v8, v9 offset1:32
	ds_write2_b32 v23, v10, v11 offset0:64 offset1:96
	ds_write2_b32 v24, v12, v13 offset1:32
	ds_write2_b32 v24, v14, v15 offset0:64 offset1:96
	s_waitcnt lgkmcnt(0)
	s_barrier
	s_and_saveexec_b64 s[0:1], s[34:35]
	s_movk_i32 s51, 0x1ff
	s_movk_i32 s58, 0x1080
	s_cbranch_execz .LBB0_1603
	s_mov_b64 s[2:3], 0
	v_mov_b32_e32 v0, v64

.LBB0_2139:
	global_load_dwordx4 v[64:67], v[38:39], off
	v_lshl_or_b32 v16, s39, 5, v81
	v_ashrrev_i32_e32 v17, 31, v16
	v_lshlrev_b64 v[4:5], 11, v[16:17]
	v_lshl_add_u64 v[30:31], v[40:41], 0, v[4:5]
	global_load_dwordx4 v[88:91], v[30:31], off
	global_load_dwordx4 v[92:95], v[38:39], off offset:32
	global_load_dwordx4 v[96:99], v[30:31], off offset:32
	global_load_dwordx4 v[100:103], v[38:39], off offset:64
	global_load_dwordx4 v[104:107], v[30:31], off offset:64
	global_load_dwordx4 v[108:111], v[38:39], off offset:96
	global_load_dwordx4 v[112:115], v[30:31], off offset:96
	global_load_dwordx4 v[116:119], v[38:39], off offset:128
	global_load_dwordx4 v[120:123], v[30:31], off offset:128
	global_load_dwordx4 v[124:127], v[38:39], off offset:160
	global_load_dwordx4 v[128:131], v[30:31], off offset:160
	global_load_dwordx4 v[132:135], v[38:39], off offset:192
	global_load_dwordx4 v[136:139], v[30:31], off offset:192
	global_load_dwordx4 v[140:143], v[38:39], off offset:224
	global_load_dwordx4 v[144:147], v[30:31], off offset:224
	v_add_u32_e32 v18, v16, v82
	v_ashrrev_i32_e32 v19, 31, v18
	v_add_u32_e32 v20, 0x4000, v18
	v_lshl_add_u64 v[18:19], v[18:19], 2, s[94:95]
	v_ashrrev_i32_e32 v21, 31, v20
	v_lshl_add_u64 v[20:21], v[20:21], 2, s[94:95]
	global_load_dword v18, v[18:19], off
	s_nop 0
	global_load_dword v17, v[20:21], off
	v_add_u32_e32 v19, 0x8000, v84
	v_add_u32_e32 v20, 0x8400, v84
	v_add_u32_e32 v21, 0x8800, v84
	v_add_u32_e32 v22, 0x8c00, v84
	s_waitcnt vmcnt(16)
	v_mfma_f32_32x32x16_bf16 v[0:15], v[64:67], v[88:91], 0
	s_waitcnt vmcnt(14)
	v_mfma_f32_32x32x16_bf16 v[0:15], v[92:95], v[96:99], v[0:15]
	s_waitcnt vmcnt(12)
	v_mfma_f32_32x32x16_bf16 v[0:15], v[100:103], v[104:107], v[0:15]
	s_waitcnt vmcnt(10)
	v_mfma_f32_32x32x16_bf16 v[0:15], v[108:111], v[112:115], v[0:15]
	s_waitcnt vmcnt(8)
	v_mfma_f32_32x32x16_bf16 v[0:15], v[116:119], v[120:123], v[0:15]
	s_waitcnt vmcnt(6)
	v_mfma_f32_32x32x16_bf16 v[0:15], v[124:127], v[128:131], v[0:15]
	s_waitcnt vmcnt(4)
	v_mfma_f32_32x32x16_bf16 v[0:15], v[132:135], v[136:139], v[0:15]
	s_waitcnt vmcnt(2)
	v_mfma_f32_32x32x16_bf16 v[0:15], v[140:143], v[144:147], v[0:15]
	s_waitcnt vmcnt(0)
	s_nop 11
	ds_write2_b32 v19, v0, v1 offset1:32
	ds_write2_b32 v19, v2, v3 offset0:64 offset1:96
	ds_write2_b32 v20, v4, v5 offset1:32
	ds_write2_b32 v20, v6, v7 offset0:64 offset1:96
	ds_write2_b32 v21, v8, v9 offset1:32
	ds_write2_b32 v21, v10, v11 offset0:64 offset1:96
	ds_write2_b32 v22, v12, v13 offset1:32
	ds_write2_b32 v22, v14, v15 offset0:64 offset1:96
	s_waitcnt lgkmcnt(0)
	s_barrier
	s_and_saveexec_b64 s[0:1], s[34:35]
	s_movk_i32 s20, 0x1ff
	s_movk_i32 s21, 0x1080
	s_cbranch_execz .LBB0_2142
	s_mov_b64 s[2:3], 0
	v_mov_b32_e32 v0, v43

.LBB0_2437:
	s_lshl_b32 s2, s28, 6
	s_lshl_b32 s29, s28, 5
	s_and_b32 s2, s2, 0xffffff00
	s_and_b32 s3, s29, 0x60
	s_or_b32 s2, s3, s2
	v_or_b32_e32 v4, s2, v80
	global_load_dwordx4 v[112:115], v[42:43], off
	v_ashrrev_i32_e32 v5, 31, v4
	v_lshlrev_b64 v[0:1], 11, v[4:5]
	v_lshl_add_u64 v[54:55], v[44:45], 0, v[0:1]
	global_load_dwordx4 v[116:119], v[54:55], off
	v_or_b32_e32 v4, 0x80, v4
	v_ashrrev_i32_e32 v5, 31, v4
	v_lshlrev_b64 v[4:5], 11, v[4:5]
	v_lshl_add_u64 v[108:109], v[44:45], 0, v[4:5]
	global_load_dwordx4 v[120:123], v[108:109], off
	global_load_dwordx4 v[124:127], v[42:43], off offset:32
	global_load_dwordx4 v[140:143], v[54:55], off offset:32
	global_load_dwordx4 v[144:147], v[108:109], off offset:32
	global_load_dwordx4 v[148:151], v[42:43], off offset:64
	v_add_u32_e32 v32, 0x8000, v82
	global_load_dwordx4 v[160:163], v[54:55], off offset:64
	global_load_dwordx4 v[164:167], v[108:109], off offset:64
	global_load_dwordx4 v[168:171], v[42:43], off offset:96
	global_load_dwordx4 v[172:175], v[54:55], off offset:96
	global_load_dwordx4 v[176:179], v[108:109], off offset:96
	global_load_dwordx4 v[180:183], v[42:43], off offset:128
	global_load_dwordx4 v[184:187], v[54:55], off offset:128
	global_load_dwordx4 v[188:191], v[108:109], off offset:128
	global_load_dwordx4 v[192:195], v[42:43], off offset:160
	global_load_dwordx4 v[196:199], v[54:55], off offset:160
	global_load_dwordx4 v[200:203], v[108:109], off offset:160
	global_load_dwordx4 v[204:207], v[42:43], off offset:192
	global_load_dwordx4 v[208:211], v[54:55], off offset:192
	global_load_dwordx4 v[220:223], v[108:109], off offset:192
	global_load_dwordx4 v[224:227], v[42:43], off offset:224
	global_load_dwordx4 v[228:231], v[54:55], off offset:224
	global_load_dwordx4 v[232:235], v[108:109], off offset:224
	global_load_dwordx2 v[36:37], v[38:39], off
	global_load_dwordx2 v[34:35], v[40:41], off
	s_waitcnt vmcnt(24)
	v_mfma_f32_32x32x16_bf16 v[0:15], v[112:115], v[116:119], 0
	s_waitcnt vmcnt(21)
	v_mfma_f32_32x32x16_bf16 v[0:15], v[124:127], v[140:143], v[0:15]
	s_waitcnt vmcnt(23)
	v_mfma_f32_32x32x16_bf16 v[16:31], v[112:115], v[120:123], 0
	s_waitcnt vmcnt(20)
	v_mfma_f32_32x32x16_bf16 v[16:31], v[124:127], v[144:147], v[16:31]
	s_waitcnt vmcnt(18)
	v_mfma_f32_32x32x16_bf16 v[0:15], v[148:151], v[160:163], v[0:15]
	s_waitcnt vmcnt(17)
	v_mfma_f32_32x32x16_bf16 v[16:31], v[148:151], v[164:167], v[16:31]
	s_waitcnt vmcnt(14)
	v_mfma_f32_32x32x16_bf16 v[16:31], v[168:171], v[176:179], v[16:31]
	s_waitcnt vmcnt(15)
	v_mfma_f32_32x32x16_bf16 v[0:15], v[168:171], v[172:175], v[0:15]
	s_waitcnt vmcnt(11)
	v_mfma_f32_32x32x16_bf16 v[16:31], v[180:183], v[188:191], v[16:31]
	s_waitcnt vmcnt(12)
	v_mfma_f32_32x32x16_bf16 v[0:15], v[180:183], v[184:187], v[0:15]
	s_waitcnt vmcnt(8)
	v_mfma_f32_32x32x16_bf16 v[16:31], v[192:195], v[200:203], v[16:31]
	s_waitcnt vmcnt(9)
	v_mfma_f32_32x32x16_bf16 v[0:15], v[192:195], v[196:199], v[0:15]
	s_waitcnt vmcnt(5)
	v_mfma_f32_32x32x16_bf16 v[16:31], v[204:207], v[220:223], v[16:31]
	s_waitcnt vmcnt(6)
	v_mfma_f32_32x32x16_bf16 v[0:15], v[204:207], v[208:211], v[0:15]
	s_waitcnt vmcnt(2)
	v_mfma_f32_32x32x16_bf16 v[16:31], v[224:227], v[232:235], v[16:31]
	s_waitcnt vmcnt(3)
	v_mfma_f32_32x32x16_bf16 v[0:15], v[224:227], v[228:231], v[0:15]
	s_waitcnt vmcnt(0)
	v_add_u32_e32 v46, 0x8400, v82
	v_add_u32_e32 v47, 0x8800, v82
	v_add_u32_e32 v48, 0x8c00, v82
	s_nop 8
	ds_write2_b32 v32, v0, v1 offset1:32
	ds_write2_b32 v32, v2, v3 offset0:64 offset1:96
	ds_write2_b32 v46, v4, v5 offset1:32
	ds_write2_b32 v46, v6, v7 offset0:64 offset1:96
	ds_write2_b32 v47, v8, v9 offset1:32
	ds_write2_b32 v47, v10, v11 offset0:64 offset1:96
	ds_write2_b32 v48, v12, v13 offset1:32
	ds_write2_b32 v48, v14, v15 offset0:64 offset1:96
	ds_write_b32 v83, v16
	ds_write_b32 v84, v17
	ds_write_b32 v85, v18
	ds_write_b32 v86, v19
	ds_write_b32 v87, v20
	ds_write_b32 v88, v21
	ds_write_b32 v89, v22
	ds_write_b32 v90, v23
	ds_write_b32 v91, v24
	ds_write_b32 v92, v25
	ds_write_b32 v93, v26
	ds_write_b32 v95, v27
	ds_write_b32 v96, v28
	ds_write_b32 v97, v29
	ds_write_b32 v98, v30
	ds_write_b32 v99, v31
	s_waitcnt lgkmcnt(0)
	s_barrier
	s_and_saveexec_b64 s[60:61], s[38:39]
	s_movk_i32 s31, 0x1080
	s_cbranch_execz .LBB0_2436
	s_mov_b64 s[2:3], 0
	v_mov_b32_e32 v0, v79

.LBB0_2755:
	global_load_dwordx4 v[48:51], v[162:163], off
	v_lshl_or_b32 v24, s29, 5, v201
	s_movk_i32 s2, 0x1600
	v_mad_i64_i32 v[30:31], s[2:3], v24, s2, v[164:165]
	global_load_dwordx4 v[52:55], v[30:31], off
	global_load_dwordx4 v[80:83], v[162:163], off offset:32
	global_load_dwordx4 v[84:87], v[30:31], off offset:32
	global_load_dwordx4 v[88:91], v[162:163], off offset:64
	global_load_dwordx4 v[92:95], v[30:31], off offset:64
	global_load_dwordx4 v[96:99], v[162:163], off offset:96
	global_load_dwordx4 v[100:103], v[30:31], off offset:96
	global_load_dwordx4 v[104:107], v[162:163], off offset:128
	global_load_dwordx4 v[108:111], v[30:31], off offset:128
	global_load_dwordx4 v[112:115], v[162:163], off offset:160
	global_load_dwordx4 v[116:119], v[30:31], off offset:160
	global_load_dwordx4 v[120:123], v[162:163], off offset:192
	global_load_dwordx4 v[124:127], v[30:31], off offset:192
	global_load_dwordx4 v[128:131], v[162:163], off offset:224
	global_load_dwordx4 v[132:135], v[30:31], off offset:224
	global_load_dwordx4 v[136:139], v[162:163], off offset:256
	global_load_dwordx4 v[140:143], v[30:31], off offset:256
	global_load_dwordx4 v[144:147], v[162:163], off offset:288
	global_load_dwordx4 v[148:151], v[30:31], off offset:288
	global_load_dwordx4 v[180:183], v[162:163], off offset:320
	global_load_dwordx4 v[184:187], v[30:31], off offset:320
	global_load_dwordx4 v[188:191], v[162:163], off offset:352
	global_load_dwordx4 v[192:195], v[30:31], off offset:352
	global_load_dwordx4 v[196:199], v[162:163], off offset:384
	global_load_dwordx4 v[220:223], v[30:31], off offset:384
	global_load_dwordx4 v[224:227], v[162:163], off offset:416
	global_load_dwordx4 v[228:231], v[30:31], off offset:416
	global_load_dwordx4 v[232:235], v[162:163], off offset:448
	global_load_dwordx4 v[236:239], v[30:31], off offset:448
	global_load_dwordx4 v[240:243], v[162:163], off offset:480
	global_load_dwordx4 v[244:247], v[30:31], off offset:480
	s_waitcnt vmcnt(30)
	v_mfma_f32_32x32x16_bf16 v[0:15], v[48:51], v[52:55], 0
	global_load_dwordx4 v[48:51], v[162:163], off offset:512
	global_load_dwordx4 v[52:55], v[30:31], off offset:512
	s_waitcnt vmcnt(30)
	v_mfma_f32_32x32x16_bf16 v[0:15], v[80:83], v[84:87], v[0:15]
	global_load_dwordx4 v[80:83], v[162:163], off offset:544
	global_load_dwordx4 v[84:87], v[30:31], off offset:544
	s_waitcnt vmcnt(30)
	v_mfma_f32_32x32x16_bf16 v[0:15], v[88:91], v[92:95], v[0:15]
	global_load_dwordx4 v[88:91], v[162:163], off offset:576
	global_load_dwordx4 v[92:95], v[30:31], off offset:576
	s_waitcnt vmcnt(30)
	v_mfma_f32_32x32x16_bf16 v[0:15], v[96:99], v[100:103], v[0:15]
	global_load_dwordx4 v[96:99], v[162:163], off offset:608
	global_load_dwordx4 v[100:103], v[30:31], off offset:608
	s_waitcnt vmcnt(30)
	v_mfma_f32_32x32x16_bf16 v[0:15], v[104:107], v[108:111], v[0:15]
	global_load_dwordx4 v[104:107], v[162:163], off offset:640
	global_load_dwordx4 v[108:111], v[30:31], off offset:640
	s_waitcnt vmcnt(30)
	v_mfma_f32_32x32x16_bf16 v[0:15], v[112:115], v[116:119], v[0:15]
	global_load_dwordx4 v[112:115], v[162:163], off offset:672
	global_load_dwordx4 v[116:119], v[30:31], off offset:672
	v_add_u32_e32 v30, 0x8c00, v204
	v_add_u32_e32 v26, v24, v202
	v_add_u32_e32 v28, 0x4000, v26
	v_ashrrev_i32_e32 v27, 31, v26
	v_ashrrev_i32_e32 v29, 31, v28
	v_lshl_add_u64 v[26:27], v[26:27], 2, s[92:93]
	v_lshl_add_u64 v[28:29], v[28:29], 2, s[92:93]
	global_load_dword v26, v[26:27], off
	s_nop 0
	global_load_dword v25, v[28:29], off
	v_add_u32_e32 v27, 0x8000, v204
	v_add_u32_e32 v28, 0x8400, v204
	v_add_u32_e32 v29, 0x8800, v204
	s_waitcnt vmcnt(32)
	v_mfma_f32_32x32x16_bf16 v[0:15], v[120:123], v[124:127], v[0:15]
	s_waitcnt vmcnt(30)
	v_mfma_f32_32x32x16_bf16 v[0:15], v[128:131], v[132:135], v[0:15]
	s_waitcnt vmcnt(28)
	v_mfma_f32_32x32x16_bf16 v[0:15], v[136:139], v[140:143], v[0:15]
	s_waitcnt vmcnt(26)
	v_mfma_f32_32x32x16_bf16 v[0:15], v[144:147], v[148:151], v[0:15]
	s_waitcnt vmcnt(24)
	v_mfma_f32_32x32x16_bf16 v[0:15], v[180:183], v[184:187], v[0:15]
	s_waitcnt vmcnt(22)
	v_mfma_f32_32x32x16_bf16 v[0:15], v[188:191], v[192:195], v[0:15]
	s_waitcnt vmcnt(20)
	v_mfma_f32_32x32x16_bf16 v[0:15], v[196:199], v[220:223], v[0:15]
	s_waitcnt vmcnt(18)
	v_mfma_f32_32x32x16_bf16 v[0:15], v[224:227], v[228:231], v[0:15]
	s_waitcnt vmcnt(16)
	v_mfma_f32_32x32x16_bf16 v[0:15], v[232:235], v[236:239], v[0:15]
	s_waitcnt vmcnt(14)
	v_mfma_f32_32x32x16_bf16 v[0:15], v[240:243], v[244:247], v[0:15]
	s_waitcnt vmcnt(12)
	v_mfma_f32_32x32x16_bf16 v[0:15], v[48:51], v[52:55], v[0:15]
	s_waitcnt vmcnt(10)
	v_mfma_f32_32x32x16_bf16 v[0:15], v[80:83], v[84:87], v[0:15]
	s_waitcnt vmcnt(8)
	v_mfma_f32_32x32x16_bf16 v[0:15], v[88:91], v[92:95], v[0:15]
	s_waitcnt vmcnt(6)
	v_mfma_f32_32x32x16_bf16 v[0:15], v[96:99], v[100:103], v[0:15]
	s_waitcnt vmcnt(4)
	v_mfma_f32_32x32x16_bf16 v[0:15], v[104:107], v[108:111], v[0:15]
	s_waitcnt vmcnt(2)
	v_mfma_f32_32x32x16_bf16 v[0:15], v[112:115], v[116:119], v[0:15]
	s_waitcnt vmcnt(0)
	s_nop 11
	ds_write2_b32 v27, v0, v1 offset1:32
	ds_write2_b32 v27, v2, v3 offset0:64 offset1:96
	ds_write2_b32 v28, v4, v5 offset1:32
	ds_write2_b32 v28, v6, v7 offset0:64 offset1:96
	ds_write2_b32 v29, v8, v9 offset1:32
	ds_write2_b32 v29, v10, v11 offset0:64 offset1:96
	ds_write2_b32 v30, v12, v13 offset1:32
	ds_write2_b32 v30, v14, v15 offset0:64 offset1:96
	s_waitcnt lgkmcnt(0)
	s_barrier
	s_and_saveexec_b64 s[38:39], s[34:35]
	s_movk_i32 s20, 0x1ff
	s_movk_i32 s36, 0x1080
	s_cbranch_execz .LBB0_2758
	s_mov_b64 s[2:3], 0
	v_mov_b32_e32 v0, v200

.LBB0_2912:
	global_load_dwordx4 v[64:67], v[162:163], off
	v_lshl_or_b32 v24, s13, 5, v201
	s_movk_i32 s1, 0x1600
	v_mad_i64_i32 v[60:61], s[2:3], v24, s1, v[164:165]
	global_load_dwordx4 v[68:71], v[60:61], off
	global_load_dwordx4 v[72:75], v[162:163], off offset:32
	global_load_dwordx4 v[76:79], v[60:61], off offset:32
	global_load_dwordx4 v[80:83], v[162:163], off offset:64
	global_load_dwordx4 v[84:87], v[60:61], off offset:64
	global_load_dwordx4 v[88:91], v[162:163], off offset:96
	v_add_u32_e32 v25, 0x8000, v204
	global_load_dwordx4 v[92:95], v[60:61], off offset:96
	global_load_dwordx4 v[96:99], v[162:163], off offset:128
	global_load_dwordx4 v[100:103], v[60:61], off offset:128
	global_load_dwordx4 v[104:107], v[162:163], off offset:160
	global_load_dwordx4 v[108:111], v[60:61], off offset:160
	global_load_dwordx4 v[112:115], v[162:163], off offset:192
	global_load_dwordx4 v[116:119], v[60:61], off offset:192
	global_load_dwordx4 v[120:123], v[162:163], off offset:224
	global_load_dwordx4 v[124:127], v[60:61], off offset:224
	global_load_dwordx4 v[136:139], v[162:163], off offset:256
	global_load_dwordx4 v[140:143], v[60:61], off offset:256
	global_load_dwordx4 v[148:151], v[162:163], off offset:288
	global_load_dwordx4 v[172:175], v[60:61], off offset:288
	global_load_dwordx4 v[176:179], v[162:163], off offset:320
	global_load_dwordx4 v[180:183], v[60:61], off offset:320
	global_load_dwordx4 v[184:187], v[162:163], off offset:352
	global_load_dwordx4 v[188:191], v[60:61], off offset:352
	global_load_dwordx4 v[192:195], v[162:163], off offset:384
	global_load_dwordx4 v[196:199], v[60:61], off offset:384
	global_load_dwordx4 v[208:211], v[162:163], off offset:416
	global_load_dwordx4 v[220:223], v[60:61], off offset:416
	global_load_dwordx4 v[224:227], v[162:163], off offset:448
	global_load_dwordx4 v[228:231], v[60:61], off offset:448
	global_load_dwordx4 v[232:235], v[162:163], off offset:480
	global_load_dwordx4 v[236:239], v[60:61], off offset:480
	global_load_dwordx4 v[240:243], v[162:163], off offset:512
	global_load_dwordx4 v[244:247], v[60:61], off offset:512
	s_waitcnt vmcnt(32)
	v_mfma_f32_32x32x16_bf16 v[0:15], v[64:67], v[68:71], 0
	global_load_dwordx4 v[64:67], v[162:163], off offset:544
	global_load_dwordx4 v[68:71], v[60:61], off offset:544
	s_waitcnt vmcnt(32)
	v_mfma_f32_32x32x16_bf16 v[0:15], v[72:75], v[76:79], v[0:15]
	global_load_dwordx4 v[72:75], v[162:163], off offset:576
	global_load_dwordx4 v[76:79], v[60:61], off offset:576
	s_waitcnt vmcnt(32)
	v_mfma_f32_32x32x16_bf16 v[0:15], v[80:83], v[84:87], v[0:15]
	global_load_dwordx4 v[80:83], v[162:163], off offset:608
	global_load_dwordx4 v[84:87], v[60:61], off offset:608
	s_waitcnt vmcnt(32)
	v_mfma_f32_32x32x16_bf16 v[0:15], v[88:91], v[92:95], v[0:15]
	global_load_dwordx4 v[88:91], v[162:163], off offset:640
	global_load_dwordx4 v[92:95], v[60:61], off offset:640
	s_waitcnt vmcnt(32)
	v_mfma_f32_32x32x16_bf16 v[0:15], v[96:99], v[100:103], v[0:15]
	global_load_dwordx4 v[96:99], v[162:163], off offset:672
	global_load_dwordx4 v[100:103], v[60:61], off offset:672
	v_add_u32_e32 v44, v24, v202
	v_add_u32_e32 v46, 0x4000, v44
	v_ashrrev_i32_e32 v45, 31, v44
	v_ashrrev_i32_e32 v47, 31, v46
	v_lshl_add_u64 v[44:45], v[44:45], 2, s[92:93]
	v_lshl_add_u64 v[46:47], v[46:47], 2, s[92:93]
	global_load_dword v44, v[44:45], off
	s_nop 0
	global_load_dword v43, v[46:47], off
	v_add_u32_e32 v45, 0x8400, v204
	v_add_u32_e32 v46, 0x8800, v204
	v_add_u32_e32 v47, 0x8c00, v204
	s_waitcnt vmcnt(34)
	v_mfma_f32_32x32x16_bf16 v[0:15], v[104:107], v[108:111], v[0:15]
	s_waitcnt vmcnt(32)
	v_mfma_f32_32x32x16_bf16 v[0:15], v[112:115], v[116:119], v[0:15]
	s_waitcnt vmcnt(30)
	v_mfma_f32_32x32x16_bf16 v[0:15], v[120:123], v[124:127], v[0:15]
	s_waitcnt vmcnt(28)
	v_mfma_f32_32x32x16_bf16 v[0:15], v[136:139], v[140:143], v[0:15]
	s_waitcnt vmcnt(26)
	v_mfma_f32_32x32x16_bf16 v[0:15], v[148:151], v[172:175], v[0:15]
	s_waitcnt vmcnt(24)
	v_mfma_f32_32x32x16_bf16 v[0:15], v[176:179], v[180:183], v[0:15]
	s_waitcnt vmcnt(22)
	v_mfma_f32_32x32x16_bf16 v[0:15], v[184:187], v[188:191], v[0:15]
	s_waitcnt vmcnt(20)
	v_mfma_f32_32x32x16_bf16 v[0:15], v[192:195], v[196:199], v[0:15]
	s_waitcnt vmcnt(18)
	v_mfma_f32_32x32x16_bf16 v[0:15], v[208:211], v[220:223], v[0:15]
	s_waitcnt vmcnt(16)
	v_mfma_f32_32x32x16_bf16 v[0:15], v[224:227], v[228:231], v[0:15]
	s_waitcnt vmcnt(14)
	v_mfma_f32_32x32x16_bf16 v[0:15], v[232:235], v[236:239], v[0:15]
	s_waitcnt vmcnt(12)
	v_mfma_f32_32x32x16_bf16 v[0:15], v[240:243], v[244:247], v[0:15]
	s_waitcnt vmcnt(10)
	v_mfma_f32_32x32x16_bf16 v[0:15], v[64:67], v[68:71], v[0:15]
	s_waitcnt vmcnt(8)
	v_mfma_f32_32x32x16_bf16 v[0:15], v[72:75], v[76:79], v[0:15]
	s_waitcnt vmcnt(6)
	v_mfma_f32_32x32x16_bf16 v[0:15], v[80:83], v[84:87], v[0:15]
	s_waitcnt vmcnt(4)
	v_mfma_f32_32x32x16_bf16 v[0:15], v[88:91], v[92:95], v[0:15]
	s_waitcnt vmcnt(2)
	v_mfma_f32_32x32x16_bf16 v[0:15], v[96:99], v[100:103], v[0:15]
	s_waitcnt vmcnt(0)
	s_nop 11
	ds_write2_b32 v25, v0, v1 offset1:32
	ds_write2_b32 v25, v2, v3 offset0:64 offset1:96
	ds_write2_b32 v45, v4, v5 offset1:32
	ds_write2_b32 v45, v6, v7 offset0:64 offset1:96
	ds_write2_b32 v46, v8, v9 offset1:32
	ds_write2_b32 v46, v10, v11 offset0:64 offset1:96
	ds_write2_b32 v47, v12, v13 offset1:32
	ds_write2_b32 v47, v14, v15 offset0:64 offset1:96
	s_waitcnt lgkmcnt(0)
	s_barrier
	s_and_saveexec_b64 s[54:55], s[34:35]
	s_movk_i32 s1, 0x1080
	s_cbranch_execz .LBB0_2915
	s_mov_b64 s[2:3], 0
	v_mov_b32_e32 v0, v200
